# GEMM K-loops: no per-segment toggles; one static s_setprio 1 for waves 0-3 for the duration of each K-loop
# speedup vs baseline: 1.0027x; 1.0027x over previous
.LBB0_252:
	s_ashr_i32 s19, s18, 31
	s_lshl_b64 s[0:1], s[18:19], 19
	s_add_u32 s20, s33, s0
	s_addc_u32 s21, s34, s1
	s_and_b64 s[0:1], s[4:5], exec
	s_cselect_b32 s19, s21, s31
	s_cselect_b32 s50, s20, s30
	s_ashr_i32 s11, s10, 31
	s_lshl_b64 s[0:1], s[10:11], 19
	s_add_u32 s22, s35, s0
	s_addc_u32 s23, s36, s1
	s_and_b64 s[0:1], s[4:5], exec
	s_cselect_b32 s11, s23, s27
	s_cselect_b32 s51, s22, s26
	s_add_u32 s0, s30, 0x40080
	s_addc_u32 s1, s31, 0
	s_add_u32 s52, s26, 0x100
	v_mov_b32_e32 v0, 0
	s_addc_u32 s53, s27, 0
	s_mov_b32 s54, -2
	v_mov_b32_e32 v1, v0
	v_mov_b32_e32 v2, v0
	v_mov_b32_e32 v3, v0
	v_mov_b32_e32 v8, v0
	v_mov_b32_e32 v9, v0
	v_mov_b32_e32 v10, v0
	v_mov_b32_e32 v11, v0
	v_mov_b32_e32 v16, v0
	v_mov_b32_e32 v17, v0
	v_mov_b32_e32 v18, v0
	v_mov_b32_e32 v19, v0
	v_mov_b32_e32 v24, v0
	v_mov_b32_e32 v25, v0
	v_mov_b32_e32 v26, v0
	v_mov_b32_e32 v27, v0
	v_mov_b32_e32 v32, v0
	v_mov_b32_e32 v33, v0
	v_mov_b32_e32 v34, v0
	v_mov_b32_e32 v35, v0
	v_mov_b32_e32 v40, v0
	v_mov_b32_e32 v41, v0
	v_mov_b32_e32 v42, v0
	v_mov_b32_e32 v43, v0
	v_mov_b32_e32 v48, v0
	v_mov_b32_e32 v49, v0
	v_mov_b32_e32 v50, v0
	v_mov_b32_e32 v51, v0
	v_mov_b32_e32 v56, v0
	v_mov_b32_e32 v57, v0
	v_mov_b32_e32 v58, v0
	v_mov_b32_e32 v59, v0
	v_mov_b32_e32 v4, v0
	v_mov_b32_e32 v5, v0
	v_mov_b32_e32 v6, v0
	v_mov_b32_e32 v7, v0
	v_mov_b32_e32 v12, v0
	v_mov_b32_e32 v13, v0
	v_mov_b32_e32 v14, v0
	v_mov_b32_e32 v15, v0
	v_mov_b32_e32 v20, v0
	v_mov_b32_e32 v21, v0
	v_mov_b32_e32 v22, v0
	v_mov_b32_e32 v23, v0
	v_mov_b32_e32 v28, v0
	v_mov_b32_e32 v29, v0
	v_mov_b32_e32 v30, v0
	v_mov_b32_e32 v31, v0
	v_mov_b32_e32 v36, v0
	v_mov_b32_e32 v37, v0
	v_mov_b32_e32 v38, v0
	v_mov_b32_e32 v39, v0
	v_mov_b32_e32 v44, v0
	v_mov_b32_e32 v45, v0
	v_mov_b32_e32 v46, v0
	v_mov_b32_e32 v47, v0
	v_mov_b32_e32 v52, v0
	v_mov_b32_e32 v53, v0
	v_mov_b32_e32 v54, v0
	v_mov_b32_e32 v55, v0
	v_mov_b32_e32 v60, v0
	v_mov_b32_e32 v61, v0
	v_mov_b32_e32 v62, v0
	v_mov_b32_e32 v63, v0
	v_mov_b32_e32 v64, v0
	v_mov_b32_e32 v65, v0
	v_mov_b32_e32 v66, v0
	v_mov_b32_e32 v67, v0
	v_mov_b32_e32 v72, v0
	v_mov_b32_e32 v73, v0
	v_mov_b32_e32 v74, v0
	v_mov_b32_e32 v75, v0
	v_mov_b32_e32 v80, v0
	v_mov_b32_e32 v81, v0
	v_mov_b32_e32 v82, v0
	v_mov_b32_e32 v83, v0
	v_mov_b32_e32 v88, v0
	v_mov_b32_e32 v89, v0
	v_mov_b32_e32 v90, v0
	v_mov_b32_e32 v91, v0
	v_mov_b32_e32 v96, v0
	v_mov_b32_e32 v97, v0
	v_mov_b32_e32 v98, v0
	v_mov_b32_e32 v99, v0
	v_mov_b32_e32 v104, v0
	v_mov_b32_e32 v105, v0
	v_mov_b32_e32 v106, v0
	v_mov_b32_e32 v107, v0
	v_mov_b32_e32 v112, v0
	v_mov_b32_e32 v113, v0
	v_mov_b32_e32 v114, v0
	v_mov_b32_e32 v115, v0
	v_mov_b32_e32 v120, v0
	v_mov_b32_e32 v121, v0
	v_mov_b32_e32 v122, v0
	v_mov_b32_e32 v123, v0
	v_mov_b32_e32 v68, v0
	v_mov_b32_e32 v69, v0
	v_mov_b32_e32 v70, v0
	v_mov_b32_e32 v71, v0
	v_mov_b32_e32 v76, v0
	v_mov_b32_e32 v77, v0
	v_mov_b32_e32 v78, v0
	v_mov_b32_e32 v79, v0
	v_mov_b32_e32 v84, v0
	v_mov_b32_e32 v85, v0
	v_mov_b32_e32 v86, v0
	v_mov_b32_e32 v87, v0
	v_mov_b32_e32 v92, v0
	v_mov_b32_e32 v93, v0
	v_mov_b32_e32 v94, v0
	v_mov_b32_e32 v95, v0
	v_mov_b32_e32 v100, v0
	v_mov_b32_e32 v101, v0
	v_mov_b32_e32 v102, v0
	v_mov_b32_e32 v103, v0
	v_mov_b32_e32 v108, v0
	v_mov_b32_e32 v109, v0
	v_mov_b32_e32 v110, v0
	v_mov_b32_e32 v111, v0
	v_mov_b32_e32 v116, v0
	v_mov_b32_e32 v117, v0
	v_mov_b32_e32 v118, v0
	v_mov_b32_e32 v119, v0
	v_mov_b32_e32 v124, v0
	v_mov_b32_e32 v125, v0
	v_mov_b32_e32 v126, v0
	v_mov_b32_e32 v127, v0
	v_readfirstlane_b32 s100, v206
	s_nop 0
	s_cmp_ge_u32 s100, 0x100
	s_cbranch_scc1 .Lprio_skip_0
	s_setprio 1

.LBB0_359:
	s_add_u32 s42, s8, 0x100
	v_mov_b32_e32 v0, 0
	s_addc_u32 s43, s9, 0
	s_mov_b32 s44, -2
	v_mov_b32_e32 v1, v0
	v_mov_b32_e32 v2, v0
	v_mov_b32_e32 v3, v0
	v_mov_b32_e32 v4, v0
	v_mov_b32_e32 v5, v0
	v_mov_b32_e32 v6, v0
	v_mov_b32_e32 v7, v0
	v_mov_b32_e32 v16, v0
	v_mov_b32_e32 v17, v0
	v_mov_b32_e32 v18, v0
	v_mov_b32_e32 v19, v0
	v_mov_b32_e32 v20, v0
	v_mov_b32_e32 v21, v0
	v_mov_b32_e32 v22, v0
	v_mov_b32_e32 v23, v0
	v_mov_b32_e32 v32, v0
	v_mov_b32_e32 v33, v0
	v_mov_b32_e32 v34, v0
	v_mov_b32_e32 v35, v0
	v_mov_b32_e32 v36, v0
	v_mov_b32_e32 v37, v0
	v_mov_b32_e32 v38, v0
	v_mov_b32_e32 v39, v0
	v_mov_b32_e32 v48, v0
	v_mov_b32_e32 v49, v0
	v_mov_b32_e32 v50, v0
	v_mov_b32_e32 v51, v0
	v_mov_b32_e32 v52, v0
	v_mov_b32_e32 v53, v0
	v_mov_b32_e32 v54, v0
	v_mov_b32_e32 v55, v0
	v_mov_b32_e32 v8, v0
	v_mov_b32_e32 v9, v0
	v_mov_b32_e32 v10, v0
	v_mov_b32_e32 v11, v0
	v_mov_b32_e32 v12, v0
	v_mov_b32_e32 v13, v0
	v_mov_b32_e32 v14, v0
	v_mov_b32_e32 v15, v0
	v_mov_b32_e32 v24, v0
	v_mov_b32_e32 v25, v0
	v_mov_b32_e32 v26, v0
	v_mov_b32_e32 v27, v0
	v_mov_b32_e32 v28, v0
	v_mov_b32_e32 v29, v0
	v_mov_b32_e32 v30, v0
	v_mov_b32_e32 v31, v0
	v_mov_b32_e32 v40, v0
	v_mov_b32_e32 v41, v0
	v_mov_b32_e32 v42, v0
	v_mov_b32_e32 v43, v0
	v_mov_b32_e32 v44, v0
	v_mov_b32_e32 v45, v0
	v_mov_b32_e32 v46, v0
	v_mov_b32_e32 v47, v0
	v_mov_b32_e32 v56, v0
	v_mov_b32_e32 v57, v0
	v_mov_b32_e32 v58, v0
	v_mov_b32_e32 v59, v0
	v_mov_b32_e32 v60, v0
	v_mov_b32_e32 v61, v0
	v_mov_b32_e32 v62, v0
	v_mov_b32_e32 v63, v0
	v_mov_b32_e32 v64, v0
	v_mov_b32_e32 v65, v0
	v_mov_b32_e32 v66, v0
	v_mov_b32_e32 v67, v0
	v_mov_b32_e32 v68, v0
	v_mov_b32_e32 v69, v0
	v_mov_b32_e32 v70, v0
	v_mov_b32_e32 v71, v0
	v_mov_b32_e32 v80, v0
	v_mov_b32_e32 v81, v0
	v_mov_b32_e32 v82, v0
	v_mov_b32_e32 v83, v0
	v_mov_b32_e32 v84, v0
	v_mov_b32_e32 v85, v0
	v_mov_b32_e32 v86, v0
	v_mov_b32_e32 v87, v0
	v_mov_b32_e32 v96, v0
	v_mov_b32_e32 v97, v0
	v_mov_b32_e32 v98, v0
	v_mov_b32_e32 v99, v0
	v_mov_b32_e32 v100, v0
	v_mov_b32_e32 v101, v0
	v_mov_b32_e32 v102, v0
	v_mov_b32_e32 v103, v0
	v_mov_b32_e32 v112, v0
	v_mov_b32_e32 v113, v0
	v_mov_b32_e32 v114, v0
	v_mov_b32_e32 v115, v0
	v_mov_b32_e32 v116, v0
	v_mov_b32_e32 v117, v0
	v_mov_b32_e32 v118, v0
	v_mov_b32_e32 v119, v0
	v_mov_b32_e32 v72, v0
	v_mov_b32_e32 v73, v0
	v_mov_b32_e32 v74, v0
	v_mov_b32_e32 v75, v0
	v_mov_b32_e32 v76, v0
	v_mov_b32_e32 v77, v0
	v_mov_b32_e32 v78, v0
	v_mov_b32_e32 v79, v0
	v_mov_b32_e32 v88, v0
	v_mov_b32_e32 v89, v0
	v_mov_b32_e32 v90, v0
	v_mov_b32_e32 v91, v0
	v_mov_b32_e32 v92, v0
	v_mov_b32_e32 v93, v0
	v_mov_b32_e32 v94, v0
	v_mov_b32_e32 v95, v0
	v_mov_b32_e32 v104, v0
	v_mov_b32_e32 v105, v0
	v_mov_b32_e32 v106, v0
	v_mov_b32_e32 v107, v0
	v_mov_b32_e32 v108, v0
	v_mov_b32_e32 v109, v0
	v_mov_b32_e32 v110, v0
	v_mov_b32_e32 v111, v0
	v_mov_b32_e32 v120, v0
	v_mov_b32_e32 v121, v0
	v_mov_b32_e32 v122, v0
	v_mov_b32_e32 v123, v0
	v_mov_b32_e32 v124, v0
	v_mov_b32_e32 v125, v0
	v_mov_b32_e32 v126, v0
	v_mov_b32_e32 v127, v0
	v_readfirstlane_b32 s100, v206
	s_nop 0
	s_cmp_ge_u32 s100, 0x100
	s_cbranch_scc1 .Lprio_skip_1
	s_setprio 1

.LBB0_587:
	s_ashr_i32 s37, s36, 31
	s_lshl_b64 s[14:15], s[36:37], 19
	s_add_u32 s38, s90, s14
	s_addc_u32 s39, s91, s15
	s_and_b64 s[14:15], s[6:7], exec
	s_cselect_b32 s9, s39, s11
	s_cselect_b32 s16, s38, s10
	s_ashr_i32 s35, s34, 31
	s_lshl_b64 s[14:15], s[34:35], 19
	s_add_u32 s40, s0, s14
	s_addc_u32 s41, s1, s15
	s_and_b64 s[14:15], s[6:7], exec
	s_cselect_b32 s17, s41, s13
	s_cselect_b32 s35, s40, s12
	s_add_u32 s10, s10, 0x40080
	s_addc_u32 s11, s11, 0
	s_add_u32 s37, s12, 0x100
	v_mov_b32_e32 v0, 0
	s_addc_u32 s42, s13, 0
	s_mov_b32 s43, -2
	v_mov_b32_e32 v1, v0
	v_mov_b32_e32 v2, v0
	s_waitcnt lgkmcnt(0)
	v_mov_b32_e32 v3, v0
	v_mov_b32_e32 v4, v0
	v_mov_b32_e32 v5, v0
	v_mov_b32_e32 v6, v0
	v_mov_b32_e32 v7, v0
	v_mov_b32_e32 v16, v0
	v_mov_b32_e32 v17, v0
	v_mov_b32_e32 v18, v0
	v_mov_b32_e32 v19, v0
	v_mov_b32_e32 v20, v0
	v_mov_b32_e32 v21, v0
	v_mov_b32_e32 v22, v0
	v_mov_b32_e32 v23, v0
	v_mov_b32_e32 v32, v0
	v_mov_b32_e32 v33, v0
	v_mov_b32_e32 v34, v0
	v_mov_b32_e32 v35, v0
	v_mov_b32_e32 v36, v0
	v_mov_b32_e32 v37, v0
	v_mov_b32_e32 v38, v0
	v_mov_b32_e32 v39, v0
	v_mov_b32_e32 v48, v0
	v_mov_b32_e32 v49, v0
	v_mov_b32_e32 v50, v0
	v_mov_b32_e32 v51, v0
	v_mov_b32_e32 v52, v0
	v_mov_b32_e32 v53, v0
	v_mov_b32_e32 v54, v0
	v_mov_b32_e32 v55, v0
	v_mov_b32_e32 v8, v0
	v_mov_b32_e32 v9, v0
	v_mov_b32_e32 v10, v0
	v_mov_b32_e32 v11, v0
	v_mov_b32_e32 v12, v0
	v_mov_b32_e32 v13, v0
	v_mov_b32_e32 v14, v0
	v_mov_b32_e32 v15, v0
	v_mov_b32_e32 v24, v0
	v_mov_b32_e32 v25, v0
	v_mov_b32_e32 v26, v0
	v_mov_b32_e32 v27, v0
	v_mov_b32_e32 v28, v0
	v_mov_b32_e32 v29, v0
	v_mov_b32_e32 v30, v0
	v_mov_b32_e32 v31, v0
	v_mov_b32_e32 v40, v0
	v_mov_b32_e32 v41, v0
	v_mov_b32_e32 v42, v0
	v_mov_b32_e32 v43, v0
	v_mov_b32_e32 v44, v0
	v_mov_b32_e32 v45, v0
	v_mov_b32_e32 v46, v0
	v_mov_b32_e32 v47, v0
	v_mov_b32_e32 v56, v0
	v_mov_b32_e32 v57, v0
	v_mov_b32_e32 v58, v0
	v_mov_b32_e32 v59, v0
	v_mov_b32_e32 v60, v0
	v_mov_b32_e32 v61, v0
	v_mov_b32_e32 v62, v0
	v_mov_b32_e32 v63, v0
	v_mov_b32_e32 v64, v0
	v_mov_b32_e32 v65, v0
	v_mov_b32_e32 v66, v0
	v_mov_b32_e32 v67, v0
	v_mov_b32_e32 v68, v0
	v_mov_b32_e32 v69, v0
	v_mov_b32_e32 v70, v0
	v_mov_b32_e32 v71, v0
	v_mov_b32_e32 v80, v0
	v_mov_b32_e32 v81, v0
	v_mov_b32_e32 v82, v0
	v_mov_b32_e32 v83, v0
	v_mov_b32_e32 v84, v0
	v_mov_b32_e32 v85, v0
	v_mov_b32_e32 v86, v0
	v_mov_b32_e32 v87, v0
	v_mov_b32_e32 v96, v0
	v_mov_b32_e32 v97, v0
	v_mov_b32_e32 v98, v0
	v_mov_b32_e32 v99, v0
	v_mov_b32_e32 v100, v0
	v_mov_b32_e32 v101, v0
	v_mov_b32_e32 v102, v0
	v_mov_b32_e32 v103, v0
	v_mov_b32_e32 v112, v0
	v_mov_b32_e32 v113, v0
	v_mov_b32_e32 v114, v0
	v_mov_b32_e32 v115, v0
	v_mov_b32_e32 v116, v0
	v_mov_b32_e32 v117, v0
	v_mov_b32_e32 v118, v0
	v_mov_b32_e32 v119, v0
	v_mov_b32_e32 v72, v0
	v_mov_b32_e32 v73, v0
	v_mov_b32_e32 v74, v0
	v_mov_b32_e32 v75, v0
	v_mov_b32_e32 v76, v0
	v_mov_b32_e32 v77, v0
	v_mov_b32_e32 v78, v0
	v_mov_b32_e32 v79, v0
	v_mov_b32_e32 v88, v0
	v_mov_b32_e32 v89, v0
	v_mov_b32_e32 v90, v0
	v_mov_b32_e32 v91, v0
	v_mov_b32_e32 v92, v0
	v_mov_b32_e32 v93, v0
	v_mov_b32_e32 v94, v0
	v_mov_b32_e32 v95, v0
	v_mov_b32_e32 v104, v0
	v_mov_b32_e32 v105, v0
	v_mov_b32_e32 v106, v0
	v_mov_b32_e32 v107, v0
	v_mov_b32_e32 v108, v0
	v_mov_b32_e32 v109, v0
	v_mov_b32_e32 v110, v0
	v_mov_b32_e32 v111, v0
	v_mov_b32_e32 v120, v0
	v_mov_b32_e32 v121, v0
	v_mov_b32_e32 v122, v0
	v_mov_b32_e32 v123, v0
	v_mov_b32_e32 v124, v0
	v_mov_b32_e32 v125, v0
	v_mov_b32_e32 v126, v0
	v_mov_b32_e32 v127, v0
	v_readfirstlane_b32 s100, v206
	s_nop 0
	s_cmp_ge_u32 s100, 0x100
	s_cbranch_scc1 .Lprio_skip_2
	s_setprio 1

.LBB0_763:
	s_ashr_i32 s21, s20, 31
	s_lshl_b64 s[22:23], s[20:21], 19
	s_add_u32 s22, s10, s22
	s_addc_u32 s23, s11, s23
	s_and_b64 s[24:25], s[8:9], exec
	s_cselect_b32 s21, s23, s27
	s_cselect_b32 s48, s22, s26
	s_ashr_i32 s19, s18, 31
	s_lshl_b64 s[24:25], s[18:19], 19
	s_add_u32 s24, s90, s24
	s_addc_u32 s25, s91, s25
	s_and_b64 s[34:35], s[8:9], exec
	s_mov_b32 s57, s49
	s_cselect_b32 s19, s25, s31
	s_cselect_b32 s49, s24, s30
	s_add_u32 s26, s26, 0x40080
	s_addc_u32 s27, s27, 0
	s_add_u32 s50, s30, 0x100
	v_mov_b32_e32 v0, 0
	s_addc_u32 s51, s31, 0
	s_mov_b32 s52, -2
	v_mov_b32_e32 v1, v0
	v_mov_b32_e32 v2, v0
	v_mov_b32_e32 v3, v0
	v_mov_b32_e32 v32, v0
	v_mov_b32_e32 v33, v0
	v_mov_b32_e32 v34, v0
	v_mov_b32_e32 v35, v0
	v_mov_b32_e32 v4, v0
	v_mov_b32_e32 v5, v0
	v_mov_b32_e32 v6, v0
	v_mov_b32_e32 v7, v0
	v_mov_b32_e32 v36, v0
	v_mov_b32_e32 v37, v0
	v_mov_b32_e32 v38, v0
	v_mov_b32_e32 v39, v0
	v_mov_b32_e32 v8, v0
	v_mov_b32_e32 v9, v0
	v_mov_b32_e32 v10, v0
	v_mov_b32_e32 v11, v0
	v_mov_b32_e32 v40, v0
	v_mov_b32_e32 v41, v0
	v_mov_b32_e32 v42, v0
	v_mov_b32_e32 v43, v0
	v_mov_b32_e32 v12, v0
	v_mov_b32_e32 v13, v0
	v_mov_b32_e32 v14, v0
	v_mov_b32_e32 v15, v0
	v_mov_b32_e32 v44, v0
	v_mov_b32_e32 v45, v0
	v_mov_b32_e32 v46, v0
	v_mov_b32_e32 v47, v0
	v_mov_b32_e32 v64, v0
	v_mov_b32_e32 v65, v0
	v_mov_b32_e32 v66, v0
	v_mov_b32_e32 v67, v0
	v_mov_b32_e32 v96, v0
	v_mov_b32_e32 v97, v0
	v_mov_b32_e32 v98, v0
	v_mov_b32_e32 v99, v0
	v_mov_b32_e32 v68, v0
	v_mov_b32_e32 v69, v0
	v_mov_b32_e32 v70, v0
	v_mov_b32_e32 v71, v0
	v_mov_b32_e32 v100, v0
	v_mov_b32_e32 v101, v0
	v_mov_b32_e32 v102, v0
	v_mov_b32_e32 v103, v0
	v_mov_b32_e32 v72, v0
	v_mov_b32_e32 v73, v0
	v_mov_b32_e32 v74, v0
	v_mov_b32_e32 v75, v0
	v_mov_b32_e32 v104, v0
	v_mov_b32_e32 v105, v0
	v_mov_b32_e32 v106, v0
	v_mov_b32_e32 v107, v0
	v_mov_b32_e32 v76, v0
	v_mov_b32_e32 v77, v0
	v_mov_b32_e32 v78, v0
	v_mov_b32_e32 v79, v0
	v_mov_b32_e32 v108, v0
	v_mov_b32_e32 v109, v0
	v_mov_b32_e32 v110, v0
	v_mov_b32_e32 v111, v0
	v_mov_b32_e32 v16, v0
	v_mov_b32_e32 v17, v0
	v_mov_b32_e32 v18, v0
	v_mov_b32_e32 v19, v0
	v_mov_b32_e32 v48, v0
	v_mov_b32_e32 v49, v0
	v_mov_b32_e32 v50, v0
	v_mov_b32_e32 v51, v0
	v_mov_b32_e32 v20, v0
	v_mov_b32_e32 v21, v0
	v_mov_b32_e32 v22, v0
	v_mov_b32_e32 v23, v0
	v_mov_b32_e32 v52, v0
	v_mov_b32_e32 v53, v0
	v_mov_b32_e32 v54, v0
	v_mov_b32_e32 v55, v0
	v_mov_b32_e32 v24, v0
	v_mov_b32_e32 v25, v0
	v_mov_b32_e32 v26, v0
	v_mov_b32_e32 v27, v0
	v_mov_b32_e32 v56, v0
	v_mov_b32_e32 v57, v0
	v_mov_b32_e32 v58, v0
	v_mov_b32_e32 v59, v0
	v_mov_b32_e32 v28, v0
	v_mov_b32_e32 v29, v0
	v_mov_b32_e32 v30, v0
	v_mov_b32_e32 v31, v0
	v_mov_b32_e32 v60, v0
	v_mov_b32_e32 v61, v0
	v_mov_b32_e32 v62, v0
	v_mov_b32_e32 v63, v0
	v_mov_b32_e32 v80, v0
	v_mov_b32_e32 v81, v0
	v_mov_b32_e32 v82, v0
	v_mov_b32_e32 v83, v0
	v_mov_b32_e32 v112, v0
	v_mov_b32_e32 v113, v0
	v_mov_b32_e32 v114, v0
	v_mov_b32_e32 v115, v0
	v_mov_b32_e32 v84, v0
	v_mov_b32_e32 v85, v0
	v_mov_b32_e32 v86, v0
	v_mov_b32_e32 v87, v0
	v_mov_b32_e32 v116, v0
	v_mov_b32_e32 v117, v0
	v_mov_b32_e32 v118, v0
	v_mov_b32_e32 v119, v0
	v_mov_b32_e32 v88, v0
	v_mov_b32_e32 v89, v0
	v_mov_b32_e32 v90, v0
	v_mov_b32_e32 v91, v0
	v_mov_b32_e32 v120, v0
	v_mov_b32_e32 v121, v0
	v_mov_b32_e32 v122, v0
	v_mov_b32_e32 v123, v0
	v_mov_b32_e32 v92, v0
	v_mov_b32_e32 v93, v0
	v_mov_b32_e32 v94, v0
	v_mov_b32_e32 v95, v0
	v_mov_b32_e32 v124, v0
	v_mov_b32_e32 v125, v0
	v_mov_b32_e32 v126, v0
	v_mov_b32_e32 v127, v0
	v_readfirstlane_b32 s100, v206
	s_nop 0
	s_cmp_ge_u32 s100, 0x100
	s_cbranch_scc1 .Lprio_skip_3
	s_setprio 1

.LBB0_1334:
	s_ashr_i32 s17, s16, 31
	s_lshl_b64 s[18:19], s[16:17], 18
	s_add_u32 s18, s33, s18
	s_addc_u32 s19, s34, s19
	s_and_b64 s[20:21], s[6:7], exec
	s_cselect_b32 s17, s19, s9
	s_cselect_b32 s49, s18, s8
	s_ashr_i32 s15, s14, 31
	s_lshl_b64 s[20:21], s[14:15], 18
	s_add_u32 s20, s35, s20
	s_addc_u32 s21, s36, s21
	s_and_b64 s[24:25], s[6:7], exec
	s_cselect_b32 s15, s21, s23
	s_cselect_b32 s50, s20, s22
	s_add_u32 s8, s8, 0x20080
	s_addc_u32 s9, s9, 0
	s_add_u32 s51, s22, 0x100
	v_mov_b32_e32 v0, 0
	s_addc_u32 s52, s23, 0
	s_mov_b32 s53, -2
	v_mov_b32_e32 v1, v0
	v_mov_b32_e32 v2, v0
	v_mov_b32_e32 v3, v0
	v_mov_b32_e32 v4, v0
	v_mov_b32_e32 v5, v0
	v_mov_b32_e32 v6, v0
	v_mov_b32_e32 v7, v0
	v_mov_b32_e32 v16, v0
	v_mov_b32_e32 v17, v0
	v_mov_b32_e32 v18, v0
	v_mov_b32_e32 v19, v0
	v_mov_b32_e32 v20, v0
	v_mov_b32_e32 v21, v0
	v_mov_b32_e32 v22, v0
	v_mov_b32_e32 v23, v0
	v_mov_b32_e32 v32, v0
	v_mov_b32_e32 v33, v0
	v_mov_b32_e32 v34, v0
	v_mov_b32_e32 v35, v0
	v_mov_b32_e32 v36, v0
	v_mov_b32_e32 v37, v0
	v_mov_b32_e32 v38, v0
	v_mov_b32_e32 v39, v0
	v_mov_b32_e32 v48, v0
	v_mov_b32_e32 v49, v0
	v_mov_b32_e32 v50, v0
	v_mov_b32_e32 v51, v0
	v_mov_b32_e32 v52, v0
	v_mov_b32_e32 v53, v0
	v_mov_b32_e32 v54, v0
	v_mov_b32_e32 v55, v0
	v_mov_b32_e32 v8, v0
	v_mov_b32_e32 v9, v0
	v_mov_b32_e32 v10, v0
	v_mov_b32_e32 v11, v0
	v_mov_b32_e32 v12, v0
	v_mov_b32_e32 v13, v0
	v_mov_b32_e32 v14, v0
	v_mov_b32_e32 v15, v0
	v_mov_b32_e32 v24, v0
	v_mov_b32_e32 v25, v0
	v_mov_b32_e32 v26, v0
	v_mov_b32_e32 v27, v0
	v_mov_b32_e32 v28, v0
	v_mov_b32_e32 v29, v0
	v_mov_b32_e32 v30, v0
	v_mov_b32_e32 v31, v0
	v_mov_b32_e32 v40, v0
	v_mov_b32_e32 v41, v0
	v_mov_b32_e32 v42, v0
	v_mov_b32_e32 v43, v0
	v_mov_b32_e32 v44, v0
	v_mov_b32_e32 v45, v0
	v_mov_b32_e32 v46, v0
	v_mov_b32_e32 v47, v0
	v_mov_b32_e32 v56, v0
	v_mov_b32_e32 v57, v0
	v_mov_b32_e32 v58, v0
	v_mov_b32_e32 v59, v0
	v_mov_b32_e32 v60, v0
	v_mov_b32_e32 v61, v0
	v_mov_b32_e32 v62, v0
	v_mov_b32_e32 v63, v0
	v_mov_b32_e32 v64, v0
	v_mov_b32_e32 v65, v0
	v_mov_b32_e32 v66, v0
	v_mov_b32_e32 v67, v0
	v_mov_b32_e32 v68, v0
	v_mov_b32_e32 v69, v0
	v_mov_b32_e32 v70, v0
	v_mov_b32_e32 v71, v0
	v_mov_b32_e32 v80, v0
	v_mov_b32_e32 v81, v0
	v_mov_b32_e32 v82, v0
	v_mov_b32_e32 v83, v0
	v_mov_b32_e32 v84, v0
	v_mov_b32_e32 v85, v0
	v_mov_b32_e32 v86, v0
	v_mov_b32_e32 v87, v0
	v_mov_b32_e32 v96, v0
	v_mov_b32_e32 v97, v0
	v_mov_b32_e32 v98, v0
	v_mov_b32_e32 v99, v0
	v_mov_b32_e32 v100, v0
	v_mov_b32_e32 v101, v0
	v_mov_b32_e32 v102, v0
	v_mov_b32_e32 v103, v0
	v_mov_b32_e32 v112, v0
	v_mov_b32_e32 v113, v0
	v_mov_b32_e32 v114, v0
	v_mov_b32_e32 v115, v0
	v_mov_b32_e32 v116, v0
	v_mov_b32_e32 v117, v0
	v_mov_b32_e32 v118, v0
	v_mov_b32_e32 v119, v0
	v_mov_b32_e32 v72, v0
	v_mov_b32_e32 v73, v0
	v_mov_b32_e32 v74, v0
	v_mov_b32_e32 v75, v0
	v_mov_b32_e32 v76, v0
	v_mov_b32_e32 v77, v0
	v_mov_b32_e32 v78, v0
	v_mov_b32_e32 v79, v0
	v_mov_b32_e32 v88, v0
	v_mov_b32_e32 v89, v0
	v_mov_b32_e32 v90, v0
	v_mov_b32_e32 v91, v0
	v_mov_b32_e32 v92, v0
	v_mov_b32_e32 v93, v0
	v_mov_b32_e32 v94, v0
	v_mov_b32_e32 v95, v0
	v_mov_b32_e32 v104, v0
	v_mov_b32_e32 v105, v0
	v_mov_b32_e32 v106, v0
	v_mov_b32_e32 v107, v0
	v_mov_b32_e32 v108, v0
	v_mov_b32_e32 v109, v0
	v_mov_b32_e32 v110, v0
	v_mov_b32_e32 v111, v0
	v_mov_b32_e32 v120, v0
	v_mov_b32_e32 v121, v0
	v_mov_b32_e32 v122, v0
	v_mov_b32_e32 v123, v0
	v_mov_b32_e32 v124, v0
	v_mov_b32_e32 v125, v0
	v_mov_b32_e32 v126, v0
	v_mov_b32_e32 v127, v0
	v_readfirstlane_b32 s100, v206
	s_nop 0
	s_cmp_ge_u32 s100, 0x100
	s_cbranch_scc1 .Lprio_skip_4
	s_setprio 1

.LBB0_1437:
	s_ashr_i32 s13, s12, 31
	s_lshl_b64 s[14:15], s[12:13], 19
	s_add_u32 s14, s24, s14
	s_addc_u32 s15, s25, s15
	s_and_b64 s[16:17], s[4:5], exec
	s_cselect_b32 s13, s15, s19
	s_cselect_b32 s44, s14, s18
	s_ashr_i32 s11, s10, 31
	s_lshl_b64 s[16:17], s[10:11], 19
	s_add_u32 s16, s26, s16
	s_addc_u32 s17, s27, s17
	s_and_b64 s[22:23], s[4:5], exec
	s_cselect_b32 s11, s17, s21
	s_cselect_b32 s45, s16, s20
	s_add_u32 s18, s18, 0x40080
	s_addc_u32 s19, s19, 0
	s_add_u32 s46, s20, 0x100
	v_mov_b32_e32 v0, 0
	s_mov_b32 s53, s49
	s_addc_u32 s47, s21, 0
	s_mov_b32 s48, -2
	v_mov_b32_e32 v1, v0
	v_mov_b32_e32 v2, v0
	v_mov_b32_e32 v3, v0
	v_mov_b32_e32 v4, v0
	v_mov_b32_e32 v5, v0
	v_mov_b32_e32 v6, v0
	v_mov_b32_e32 v7, v0
	v_mov_b32_e32 v16, v0
	v_mov_b32_e32 v17, v0
	v_mov_b32_e32 v18, v0
	v_mov_b32_e32 v19, v0
	v_mov_b32_e32 v20, v0
	v_mov_b32_e32 v21, v0
	v_mov_b32_e32 v22, v0
	v_mov_b32_e32 v23, v0
	v_mov_b32_e32 v32, v0
	v_mov_b32_e32 v33, v0
	v_mov_b32_e32 v34, v0
	v_mov_b32_e32 v35, v0
	v_mov_b32_e32 v36, v0
	v_mov_b32_e32 v37, v0
	v_mov_b32_e32 v38, v0
	v_mov_b32_e32 v39, v0
	v_mov_b32_e32 v48, v0
	v_mov_b32_e32 v49, v0
	v_mov_b32_e32 v50, v0
	v_mov_b32_e32 v51, v0
	v_mov_b32_e32 v52, v0
	v_mov_b32_e32 v53, v0
	v_mov_b32_e32 v54, v0
	v_mov_b32_e32 v55, v0
	v_mov_b32_e32 v8, v0
	v_mov_b32_e32 v9, v0
	v_mov_b32_e32 v10, v0
	v_mov_b32_e32 v11, v0
	v_mov_b32_e32 v12, v0
	v_mov_b32_e32 v13, v0
	v_mov_b32_e32 v14, v0
	v_mov_b32_e32 v15, v0
	v_mov_b32_e32 v24, v0
	v_mov_b32_e32 v25, v0
	v_mov_b32_e32 v26, v0
	v_mov_b32_e32 v27, v0
	v_mov_b32_e32 v28, v0
	v_mov_b32_e32 v29, v0
	v_mov_b32_e32 v30, v0
	v_mov_b32_e32 v31, v0
	v_mov_b32_e32 v40, v0
	v_mov_b32_e32 v41, v0
	v_mov_b32_e32 v42, v0
	v_mov_b32_e32 v43, v0
	v_mov_b32_e32 v44, v0
	v_mov_b32_e32 v45, v0
	v_mov_b32_e32 v46, v0
	v_mov_b32_e32 v47, v0
	v_mov_b32_e32 v56, v0
	v_mov_b32_e32 v57, v0
	v_mov_b32_e32 v58, v0
	v_mov_b32_e32 v59, v0
	v_mov_b32_e32 v60, v0
	v_mov_b32_e32 v61, v0
	v_mov_b32_e32 v62, v0
	v_mov_b32_e32 v63, v0
	v_mov_b32_e32 v64, v0
	v_mov_b32_e32 v65, v0
	v_mov_b32_e32 v66, v0
	v_mov_b32_e32 v67, v0
	v_mov_b32_e32 v68, v0
	v_mov_b32_e32 v69, v0
	v_mov_b32_e32 v70, v0
	v_mov_b32_e32 v71, v0
	v_mov_b32_e32 v80, v0
	v_mov_b32_e32 v81, v0
	v_mov_b32_e32 v82, v0
	v_mov_b32_e32 v83, v0
	v_mov_b32_e32 v84, v0
	v_mov_b32_e32 v85, v0
	v_mov_b32_e32 v86, v0
	v_mov_b32_e32 v87, v0
	v_mov_b32_e32 v96, v0
	v_mov_b32_e32 v97, v0
	v_mov_b32_e32 v98, v0
	v_mov_b32_e32 v99, v0
	v_mov_b32_e32 v100, v0
	v_mov_b32_e32 v101, v0
	v_mov_b32_e32 v102, v0
	v_mov_b32_e32 v103, v0
	v_mov_b32_e32 v112, v0
	v_mov_b32_e32 v113, v0
	v_mov_b32_e32 v114, v0
	v_mov_b32_e32 v115, v0
	v_mov_b32_e32 v116, v0
	v_mov_b32_e32 v117, v0
	v_mov_b32_e32 v118, v0
	v_mov_b32_e32 v119, v0
	v_mov_b32_e32 v72, v0
	v_mov_b32_e32 v73, v0
	v_mov_b32_e32 v74, v0
	v_mov_b32_e32 v75, v0
	v_mov_b32_e32 v76, v0
	v_mov_b32_e32 v77, v0
	v_mov_b32_e32 v78, v0
	v_mov_b32_e32 v79, v0
	v_mov_b32_e32 v88, v0
	v_mov_b32_e32 v89, v0
	v_mov_b32_e32 v90, v0
	v_mov_b32_e32 v91, v0
	v_mov_b32_e32 v92, v0
	v_mov_b32_e32 v93, v0
	v_mov_b32_e32 v94, v0
	v_mov_b32_e32 v95, v0
	v_mov_b32_e32 v104, v0
	v_mov_b32_e32 v105, v0
	v_mov_b32_e32 v106, v0
	v_mov_b32_e32 v107, v0
	v_mov_b32_e32 v108, v0
	v_mov_b32_e32 v109, v0
	v_mov_b32_e32 v110, v0
	v_mov_b32_e32 v111, v0
	v_mov_b32_e32 v120, v0
	v_mov_b32_e32 v121, v0
	v_mov_b32_e32 v122, v0
	v_mov_b32_e32 v123, v0
	v_mov_b32_e32 v124, v0
	v_mov_b32_e32 v125, v0
	v_mov_b32_e32 v126, v0
	v_mov_b32_e32 v127, v0
	v_readfirstlane_b32 s100, v206
	s_nop 0
	s_cmp_ge_u32 s100, 0x100
	s_cbranch_scc1 .Lprio_skip_5
	s_setprio 1
